# residual GEMM epilogue: bf16 write-through stores merged to 16 bytes per lane via permlane16 swap (phases 2/8/10/12/18)
# speedup vs baseline: 1.0316x; 1.0209x over previous
.LBB0_608:
	s_andn2_b64 vcc, exec, s[12:13]
	s_cbranch_vccnz .LBB0_610
	v_lshlrev_b32_e32 v254, 1, v144
	v_cvt_pk_bf16_f32 v250, v124, v125
	v_cvt_pk_bf16_f32 v251, v126, v127

.LBB0_612:
	s_andn2_b64 vcc, exec, s[12:13]
	s_cbranch_vccnz .LBB0_614
	v_cvt_pk_bf16_f32 v252, v120, v121
	v_cvt_pk_bf16_f32 v253, v122, v123
	v_and_b32_e32 v150, 16, v197
	v_lshrrev_b32_e32 v151, 1, v150
	v_add3_u32 v254, v254, v150, v151
	v_permlane16_swap_b32_e32 v250, v252
	v_permlane16_swap_b32_e32 v251, v253
	buffer_store_dwordx4 v[250:253], v254, s[24:27], 0 offen sc1

.LBB0_616:
	s_andn2_b64 vcc, exec, s[12:13]
	s_cbranch_vccnz .LBB0_618
	v_lshlrev_b32_e32 v254, 1, v145
	v_cvt_pk_bf16_f32 v250, v116, v117
	v_cvt_pk_bf16_f32 v251, v118, v119

.LBB0_620:
	s_andn2_b64 vcc, exec, s[12:13]
	s_cbranch_vccnz .LBB0_622
	v_cvt_pk_bf16_f32 v252, v112, v113
	v_cvt_pk_bf16_f32 v253, v114, v115
	v_and_b32_e32 v150, 16, v197
	v_lshrrev_b32_e32 v151, 1, v150
	v_add3_u32 v254, v254, v150, v151
	v_permlane16_swap_b32_e32 v250, v252
	v_permlane16_swap_b32_e32 v251, v253
	buffer_store_dwordx4 v[250:253], v254, s[24:27], 0 offen sc1

.LBB0_628:
	s_andn2_b64 vcc, exec, s[72:73]
	s_cbranch_vccnz .LBB0_630
	v_lshlrev_b32_e32 v254, 1, v114
	v_cvt_pk_bf16_f32 v250, v108, v109
	v_cvt_pk_bf16_f32 v251, v110, v111

.LBB0_632:
	s_andn2_b64 vcc, exec, s[72:73]
	s_cbranch_vccnz .LBB0_634
	v_cvt_pk_bf16_f32 v252, v104, v105
	v_cvt_pk_bf16_f32 v253, v106, v107
	v_and_b32_e32 v116, 16, v197
	v_lshrrev_b32_e32 v117, 1, v116
	v_add3_u32 v254, v254, v116, v117
	v_permlane16_swap_b32_e32 v250, v252
	v_permlane16_swap_b32_e32 v251, v253
	buffer_store_dwordx4 v[250:253], v254, s[24:27], 0 offen sc1

.LBB0_636:
	s_andn2_b64 vcc, exec, s[72:73]
	s_cbranch_vccnz .LBB0_638
	v_lshlrev_b32_e32 v254, 1, v115
	v_cvt_pk_bf16_f32 v250, v100, v101
	v_cvt_pk_bf16_f32 v251, v102, v103

.LBB0_642:
	v_cvt_pk_bf16_f32 v252, v96, v97
	v_cvt_pk_bf16_f32 v253, v98, v99
	v_and_b32_e32 v116, 16, v197
	v_lshrrev_b32_e32 v117, 1, v116
	v_add3_u32 v254, v254, v116, v117
	v_permlane16_swap_b32_e32 v250, v252
	v_permlane16_swap_b32_e32 v251, v253
	buffer_store_dwordx4 v[250:253], v254, s[24:27], 0 offen sc1
	s_and_b64 vcc, exec, s[12:13]
	s_cbranch_vccnz .LBB0_646

.LBB0_648:
	s_andn2_b64 vcc, exec, s[72:73]
	s_cbranch_vccnz .LBB0_650
	v_lshlrev_b32_e32 v254, 1, v98
	v_cvt_pk_bf16_f32 v250, v92, v93
	v_cvt_pk_bf16_f32 v251, v94, v95

.LBB0_652:
	s_andn2_b64 vcc, exec, s[72:73]
	s_cbranch_vccnz .LBB0_654
	v_cvt_pk_bf16_f32 v252, v88, v89
	v_cvt_pk_bf16_f32 v253, v90, v91
	v_and_b32_e32 v100, 16, v197
	v_lshrrev_b32_e32 v101, 1, v100
	v_add3_u32 v254, v254, v100, v101
	v_permlane16_swap_b32_e32 v250, v252
	v_permlane16_swap_b32_e32 v251, v253
	buffer_store_dwordx4 v[250:253], v254, s[24:27], 0 offen sc1

.LBB0_656:
	s_andn2_b64 vcc, exec, s[72:73]
	s_cbranch_vccnz .LBB0_658
	v_lshlrev_b32_e32 v254, 1, v99
	v_cvt_pk_bf16_f32 v250, v84, v85
	v_cvt_pk_bf16_f32 v251, v86, v87

.LBB0_662:
	v_cvt_pk_bf16_f32 v252, v80, v81
	v_cvt_pk_bf16_f32 v253, v82, v83
	v_and_b32_e32 v100, 16, v197
	v_lshrrev_b32_e32 v101, 1, v100
	v_add3_u32 v254, v254, v100, v101
	v_permlane16_swap_b32_e32 v250, v252
	v_permlane16_swap_b32_e32 v251, v253
	buffer_store_dwordx4 v[250:253], v254, s[24:27], 0 offen sc1
	s_and_b64 vcc, exec, s[12:13]
	s_cbranch_vccnz .LBB0_666

.LBB0_668:
	s_andn2_b64 vcc, exec, s[72:73]
	s_cbranch_vccnz .LBB0_670
	v_lshlrev_b32_e32 v254, 1, v82
	v_cvt_pk_bf16_f32 v250, v76, v77
	v_cvt_pk_bf16_f32 v251, v78, v79

.LBB0_672:
	s_andn2_b64 vcc, exec, s[72:73]
	s_cbranch_vccnz .LBB0_674
	v_cvt_pk_bf16_f32 v252, v72, v73
	v_cvt_pk_bf16_f32 v253, v74, v75
	v_and_b32_e32 v84, 16, v197
	v_lshrrev_b32_e32 v85, 1, v84
	v_add3_u32 v254, v254, v84, v85
	v_permlane16_swap_b32_e32 v250, v252
	v_permlane16_swap_b32_e32 v251, v253
	buffer_store_dwordx4 v[250:253], v254, s[24:27], 0 offen sc1

.LBB0_676:
	s_andn2_b64 vcc, exec, s[72:73]
	s_cbranch_vccnz .LBB0_678
	v_lshlrev_b32_e32 v254, 1, v83
	v_cvt_pk_bf16_f32 v250, v68, v69
	v_cvt_pk_bf16_f32 v251, v70, v71

.LBB0_682:
	v_cvt_pk_bf16_f32 v252, v64, v65
	v_cvt_pk_bf16_f32 v253, v66, v67
	v_and_b32_e32 v84, 16, v197
	v_lshrrev_b32_e32 v85, 1, v84
	v_add3_u32 v254, v254, v84, v85
	v_permlane16_swap_b32_e32 v250, v252
	v_permlane16_swap_b32_e32 v251, v253
	buffer_store_dwordx4 v[250:253], v254, s[24:27], 0 offen sc1
	s_and_b64 vcc, exec, s[12:13]
	s_cbranch_vccnz .LBB0_686

.LBB0_688:
	s_andn2_b64 vcc, exec, s[72:73]
	s_cbranch_vccnz .LBB0_690
	v_lshlrev_b32_e32 v254, 1, v66
	v_cvt_pk_bf16_f32 v250, v60, v61
	v_cvt_pk_bf16_f32 v251, v62, v63

.LBB0_692:
	s_andn2_b64 vcc, exec, s[72:73]
	s_cbranch_vccnz .LBB0_694
	v_cvt_pk_bf16_f32 v252, v56, v57
	v_cvt_pk_bf16_f32 v253, v58, v59
	v_and_b32_e32 v68, 16, v197
	v_lshrrev_b32_e32 v69, 1, v68
	v_add3_u32 v254, v254, v68, v69
	v_permlane16_swap_b32_e32 v250, v252
	v_permlane16_swap_b32_e32 v251, v253
	buffer_store_dwordx4 v[250:253], v254, s[24:27], 0 offen sc1

.LBB0_696:
	s_andn2_b64 vcc, exec, s[72:73]
	s_cbranch_vccnz .LBB0_698
	v_lshlrev_b32_e32 v254, 1, v67
	v_cvt_pk_bf16_f32 v250, v52, v53
	v_cvt_pk_bf16_f32 v251, v54, v55

.LBB0_702:
	v_cvt_pk_bf16_f32 v252, v48, v49
	v_cvt_pk_bf16_f32 v253, v50, v51
	v_and_b32_e32 v68, 16, v197
	v_lshrrev_b32_e32 v69, 1, v68
	v_add3_u32 v254, v254, v68, v69
	v_permlane16_swap_b32_e32 v250, v252
	v_permlane16_swap_b32_e32 v251, v253
	buffer_store_dwordx4 v[250:253], v254, s[24:27], 0 offen sc1
	s_and_b64 vcc, exec, s[12:13]
	s_cbranch_vccnz .LBB0_706

.LBB0_708:
	s_andn2_b64 vcc, exec, s[72:73]
	s_cbranch_vccnz .LBB0_710
	v_lshlrev_b32_e32 v254, 1, v50
	v_cvt_pk_bf16_f32 v250, v44, v45
	v_cvt_pk_bf16_f32 v251, v46, v47

.LBB0_712:
	s_andn2_b64 vcc, exec, s[72:73]
	s_cbranch_vccnz .LBB0_714
	v_cvt_pk_bf16_f32 v252, v40, v41
	v_cvt_pk_bf16_f32 v253, v42, v43
	v_and_b32_e32 v52, 16, v197
	v_lshrrev_b32_e32 v53, 1, v52
	v_add3_u32 v254, v254, v52, v53
	v_permlane16_swap_b32_e32 v250, v252
	v_permlane16_swap_b32_e32 v251, v253
	buffer_store_dwordx4 v[250:253], v254, s[24:27], 0 offen sc1

.LBB0_716:
	s_andn2_b64 vcc, exec, s[72:73]
	s_cbranch_vccnz .LBB0_718
	v_lshlrev_b32_e32 v254, 1, v51
	v_cvt_pk_bf16_f32 v250, v36, v37
	v_cvt_pk_bf16_f32 v251, v38, v39

.LBB0_722:
	v_cvt_pk_bf16_f32 v252, v32, v33
	v_cvt_pk_bf16_f32 v253, v34, v35
	v_and_b32_e32 v52, 16, v197
	v_lshrrev_b32_e32 v53, 1, v52
	v_add3_u32 v254, v254, v52, v53
	v_permlane16_swap_b32_e32 v250, v252
	v_permlane16_swap_b32_e32 v251, v253
	buffer_store_dwordx4 v[250:253], v254, s[24:27], 0 offen sc1
	s_and_b64 vcc, exec, s[12:13]
	s_cbranch_vccnz .LBB0_726

.LBB0_728:
	s_andn2_b64 vcc, exec, s[72:73]
	s_cbranch_vccnz .LBB0_730
	v_lshlrev_b32_e32 v254, 1, v34
	v_cvt_pk_bf16_f32 v250, v28, v29
	v_cvt_pk_bf16_f32 v251, v30, v31

.LBB0_732:
	s_andn2_b64 vcc, exec, s[72:73]
	s_cbranch_vccnz .LBB0_734
	v_cvt_pk_bf16_f32 v252, v24, v25
	v_cvt_pk_bf16_f32 v253, v26, v27
	v_and_b32_e32 v36, 16, v197
	v_lshrrev_b32_e32 v37, 1, v36
	v_add3_u32 v254, v254, v36, v37
	v_permlane16_swap_b32_e32 v250, v252
	v_permlane16_swap_b32_e32 v251, v253
	buffer_store_dwordx4 v[250:253], v254, s[24:27], 0 offen sc1

.LBB0_736:
	s_andn2_b64 vcc, exec, s[72:73]
	s_cbranch_vccnz .LBB0_738
	v_lshlrev_b32_e32 v254, 1, v35
	v_cvt_pk_bf16_f32 v250, v20, v21
	v_cvt_pk_bf16_f32 v251, v22, v23

.LBB0_742:
	v_cvt_pk_bf16_f32 v252, v16, v17
	v_cvt_pk_bf16_f32 v253, v18, v19
	v_and_b32_e32 v36, 16, v197
	v_lshrrev_b32_e32 v37, 1, v36
	v_add3_u32 v254, v254, v36, v37
	v_permlane16_swap_b32_e32 v250, v252
	v_permlane16_swap_b32_e32 v251, v253
	buffer_store_dwordx4 v[250:253], v254, s[24:27], 0 offen sc1
	s_and_b64 vcc, exec, s[12:13]
	s_cbranch_vccnz .LBB0_746

.LBB0_748:
	s_andn2_b64 vcc, exec, s[72:73]
	s_cbranch_vccnz .LBB0_750
	v_lshlrev_b32_e32 v254, 1, v18
	v_cvt_pk_bf16_f32 v250, v12, v13
	v_cvt_pk_bf16_f32 v251, v14, v15

.LBB0_752:
	s_andn2_b64 vcc, exec, s[72:73]
	s_cbranch_vccnz .LBB0_754
	v_cvt_pk_bf16_f32 v252, v8, v9
	v_cvt_pk_bf16_f32 v253, v10, v11
	v_and_b32_e32 v20, 16, v197
	v_lshrrev_b32_e32 v21, 1, v20
	v_add3_u32 v254, v254, v20, v21
	v_permlane16_swap_b32_e32 v250, v252
	v_permlane16_swap_b32_e32 v251, v253
	buffer_store_dwordx4 v[250:253], v254, s[24:27], 0 offen sc1

.LBB0_756:
	s_andn2_b64 vcc, exec, s[72:73]
	s_cbranch_vccnz .LBB0_758
	v_lshlrev_b32_e32 v254, 1, v19
	v_cvt_pk_bf16_f32 v250, v4, v5
	v_cvt_pk_bf16_f32 v251, v6, v7

.LBB0_763:
	v_cvt_pk_bf16_f32 v252, v0, v1
	v_cvt_pk_bf16_f32 v253, v2, v3
	v_and_b32_e32 v20, 16, v197
	v_lshrrev_b32_e32 v21, 1, v20
	v_add3_u32 v254, v254, v20, v21
	v_permlane16_swap_b32_e32 v250, v252
	v_permlane16_swap_b32_e32 v251, v253
	buffer_store_dwordx4 v[250:253], v254, s[24:27], 0 offen sc1
	s_and_b64 vcc, exec, s[12:13]
	s_cbranch_vccnz .LBB0_761
